# slot role split by XCD bit 1 (XCDs 2,3,6,7 run in-proj first) instead of bit 0
# baseline (speedup 1.0000x reference)
; #define LND asm volatile("" : "+s"(l), "+s"(pass))
; __global__ void __launch_bounds__(256, 2) fwd_megakernel(Params P) {
;     ...
;     const int role = ROLE_SPLIT ? ((blockIdx.x >> 8) & 1) : ROLE_ALL;
; #pragma unroll 1
;     for (int it = 0; it < 3; ++it) {
; #pragma unroll 1
;       for (int step = 0; step < 2; ++step) {
;         int pass;
;         if ((step ^ role) == 0) {
;           if (it < 2) { pass = __builtin_amdgcn_readfirstlane(it); LND; phase_inproj(P, l, pass, smem); }
;         } else {
;           if (it > 0) { pass = __builtin_amdgcn_readfirstlane(it - 1); LND; phase11(P, l, pass, smem); }
;         }
;       }
.LBB0_123:
	s_cmp_lg_u32 s51, 0
	s_cselect_b64 s[26:27], -1, 0
	s_cmp_eq_u32 s51, 2
	s_cselect_b64 s[4:5], -1, 0
	v_writelane_b32 v252, s4, 34
	s_cmp_lg_u32 s51, 2
	s_cselect_b64 s[6:7], -1, 0
	v_writelane_b32 v252, s5, 35
	v_writelane_b32 v252, s51, 36
	s_mov_b64 s[72:73], -1
	s_mov_b32 s2, s0
	v_writelane_b32 v252, s6, 37
	s_nop 1
	v_writelane_b32 v252, s7, 38
	s_mov_b64 s[40:41], -1
	s_getreg_b32 vcc_lo, hwreg(HW_REG_XCC_ID, 0, 4)
	s_nop 1
	s_bitcmp1_b32 vcc_lo, 1
	s_cbranch_scc1 .LBB0_277
	s_branch .LBB0_125
.Lsplit_latch:
	s_getreg_b32 vcc_lo, hwreg(HW_REG_XCC_ID, 0, 4)
	s_nop 1
	s_bitcmp1_b32 vcc_lo, 1
	s_cbranch_scc0 .LBB0_124
	s_waitcnt vmcnt(0) lgkmcnt(0)
	s_barrier
	v_readlane_b32 s51, v252, 36
	s_mov_b32 s2, s0
	s_nop 1
	s_cmp_lg_u32 s51, 0
	s_cselect_b64 s[26:27], -1, 0
	s_branch .LBB0_125
